# out-proj context rows via direct global-load MFMA streaming, 8 K-steps in flight
# speedup vs baseline: 1.0082x; 1.0082x over previous
.LBB0_90:
	s_andn2_b64 vcc, exec, s[2:3]
	s_cbranch_vccnz .LBB0_93
	v_readlane_b32 s2, v252, 20
	v_readlane_b32 s3, v252, 21
	v_readlane_b32 s5, v255, 19
	v_readlane_b32 s8, v252, 0
	s_nop 0
	s_sub_u32 s2, s2, 0x1c0
	s_subb_u32 s3, s3, 0
	s_sub_i32 s5, s5, 3
	s_lshr_b32 s5, s5, 3
	v_and_b32_e32 v0, 63, v220
	v_and_b32_e32 v1, 15, v0
	v_lshrrev_b32_e32 v12, 4, v0
	v_lshrrev_b32_e32 v13, 6, v220
	v_lshrrev_b32_e32 v14, 1, v13
	v_and_b32_e32 v13, 1, v13
	s_and_b32 s10, s8, 31
	s_lshl_b32 s10, s10, 5
	s_lshr_b32 s11, s8, 5
	s_lshl_b32 s11, s11, 5
	s_addk_i32 s11, 0x4000
	v_lshlrev_b32_e32 v14, 4, v14
	v_add_u32_e32 v14, s10, v14
	v_add_u32_e32 v15, v14, v1
	v_lshl_add_u32 v13, v13, 4, v1
	v_add_u32_e32 v13, s11, v13
	s_mov_b32 s10, 0x800
	v_lshlrev_b32_e32 v16, 4, v12
	v_mul_lo_u32 v15, v15, s10
	v_mul_lo_u32 v17, v13, s10
	v_add_u32_e32 v15, v15, v16
	v_add_u32_e32 v17, v17, v16
	v_lshl_add_u32 v14, v12, 2, v14
	v_lshlrev_b32_e32 v13, 10, v13
	v_add_u32_e32 v13, v13, v14
	v_lshlrev_b32_e32 v13, 1, v13
	s_load_dwordx2 s[10:11], s[2:3], 0xf0
	s_mul_i32 s8, s5, 0x200000
	s_waitcnt lgkmcnt(0)
	s_add_u32 s10, s10, s8
	s_addc_u32 s11, s11, 0
	v_mov_b32_e32 v192, v15
	v_lshl_add_u64 v[2:3], v[192:193], 0, s[10:11]
	s_load_dwordx2 s[10:11], s[2:3], 0x148
	s_waitcnt lgkmcnt(0)
	v_mov_b32_e32 v192, v17
	v_lshl_add_u64 v[4:5], v[192:193], 0, s[10:11]
	s_load_dwordx2 s[10:11], s[2:3], 0x140
	s_waitcnt lgkmcnt(0)
	v_mov_b32_e32 v192, v13
	v_lshl_add_u64 v[6:7], v[192:193], 0, s[10:11]
	v_mov_b32_e32 v8, 0
	v_mov_b32_e32 v9, 0
	v_mov_b32_e32 v10, 0
	v_mov_b32_e32 v11, 0
	global_load_dwordx4 v[58:61], v[2:3], off
	global_load_dwordx4 v[62:65], v[4:5], off
	global_load_dwordx4 v[66:69], v[2:3], off offset:64
	global_load_dwordx4 v[70:73], v[4:5], off offset:64
	global_load_dwordx4 v[74:77], v[2:3], off offset:128
	global_load_dwordx4 v[78:81], v[4:5], off offset:128
	global_load_dwordx4 v[82:85], v[2:3], off offset:192
	global_load_dwordx4 v[86:89], v[4:5], off offset:192
	global_load_dwordx4 v[90:93], v[2:3], off offset:256
	global_load_dwordx4 v[94:97], v[4:5], off offset:256
	global_load_dwordx4 v[98:101], v[2:3], off offset:320
	global_load_dwordx4 v[102:105], v[4:5], off offset:320
	global_load_dwordx4 v[106:109], v[2:3], off offset:384
	global_load_dwordx4 v[110:113], v[4:5], off offset:384
	global_load_dwordx4 v[114:117], v[2:3], off offset:448
	global_load_dwordx4 v[118:121], v[4:5], off offset:448
	global_load_dwordx4 v[122:125], v[2:3], off offset:512
	global_load_dwordx4 v[126:129], v[4:5], off offset:512
	global_load_dwordx4 v[130:133], v[2:3], off offset:576
	global_load_dwordx4 v[134:137], v[4:5], off offset:576
	global_load_dwordx4 v[138:141], v[2:3], off offset:640
	global_load_dwordx4 v[142:145], v[4:5], off offset:640
	global_load_dwordx4 v[146:149], v[2:3], off offset:704
	global_load_dwordx4 v[150:153], v[4:5], off offset:704
	global_load_dwordx4 v[154:157], v[2:3], off offset:768
	global_load_dwordx4 v[158:161], v[4:5], off offset:768
	global_load_dwordx4 v[162:165], v[2:3], off offset:832
	global_load_dwordx4 v[166:169], v[4:5], off offset:832
	global_load_dwordx4 v[170:173], v[2:3], off offset:896
	global_load_dwordx4 v[174:177], v[4:5], off offset:896
	global_load_dwordx4 v[178:181], v[2:3], off offset:960
	global_load_dwordx4 v[182:185], v[4:5], off offset:960
	s_mov_b32 s8, 1
	s_mov_b64 s[10:11], 0x400
.Lctxo_loop:
	v_lshl_add_u64 v[2:3], v[2:3], 0, s[10:11]
	v_lshl_add_u64 v[4:5], v[4:5], 0, s[10:11]
	s_waitcnt vmcnt(28)
	v_mfma_f32_16x16x32_bf16 v[8:11], v[58:61], v[62:65], v[8:11]
	v_mfma_f32_16x16x32_bf16 v[8:11], v[66:69], v[70:73], v[8:11]
	global_load_dwordx4 v[58:61], v[2:3], off
	global_load_dwordx4 v[62:65], v[4:5], off
	global_load_dwordx4 v[66:69], v[2:3], off offset:64
	global_load_dwordx4 v[70:73], v[4:5], off offset:64
	s_waitcnt vmcnt(28)
	v_mfma_f32_16x16x32_bf16 v[8:11], v[74:77], v[78:81], v[8:11]
	v_mfma_f32_16x16x32_bf16 v[8:11], v[82:85], v[86:89], v[8:11]
	global_load_dwordx4 v[74:77], v[2:3], off offset:128
	global_load_dwordx4 v[78:81], v[4:5], off offset:128
	global_load_dwordx4 v[82:85], v[2:3], off offset:192
	global_load_dwordx4 v[86:89], v[4:5], off offset:192
	s_waitcnt vmcnt(28)
	v_mfma_f32_16x16x32_bf16 v[8:11], v[90:93], v[94:97], v[8:11]
	v_mfma_f32_16x16x32_bf16 v[8:11], v[98:101], v[102:105], v[8:11]
	global_load_dwordx4 v[90:93], v[2:3], off offset:256
	global_load_dwordx4 v[94:97], v[4:5], off offset:256
	global_load_dwordx4 v[98:101], v[2:3], off offset:320
	global_load_dwordx4 v[102:105], v[4:5], off offset:320
	s_waitcnt vmcnt(28)
	v_mfma_f32_16x16x32_bf16 v[8:11], v[106:109], v[110:113], v[8:11]
	v_mfma_f32_16x16x32_bf16 v[8:11], v[114:117], v[118:121], v[8:11]
	global_load_dwordx4 v[106:109], v[2:3], off offset:384
	global_load_dwordx4 v[110:113], v[4:5], off offset:384
	global_load_dwordx4 v[114:117], v[2:3], off offset:448
	global_load_dwordx4 v[118:121], v[4:5], off offset:448
	s_waitcnt vmcnt(28)
	v_mfma_f32_16x16x32_bf16 v[8:11], v[122:125], v[126:129], v[8:11]
	v_mfma_f32_16x16x32_bf16 v[8:11], v[130:133], v[134:137], v[8:11]
	global_load_dwordx4 v[122:125], v[2:3], off offset:512
	global_load_dwordx4 v[126:129], v[4:5], off offset:512
	global_load_dwordx4 v[130:133], v[2:3], off offset:576
	global_load_dwordx4 v[134:137], v[4:5], off offset:576
	s_waitcnt vmcnt(28)
	v_mfma_f32_16x16x32_bf16 v[8:11], v[138:141], v[142:145], v[8:11]
	v_mfma_f32_16x16x32_bf16 v[8:11], v[146:149], v[150:153], v[8:11]
	global_load_dwordx4 v[138:141], v[2:3], off offset:640
	global_load_dwordx4 v[142:145], v[4:5], off offset:640
	global_load_dwordx4 v[146:149], v[2:3], off offset:704
	global_load_dwordx4 v[150:153], v[4:5], off offset:704
	s_waitcnt vmcnt(28)
	v_mfma_f32_16x16x32_bf16 v[8:11], v[154:157], v[158:161], v[8:11]
	v_mfma_f32_16x16x32_bf16 v[8:11], v[162:165], v[166:169], v[8:11]
	global_load_dwordx4 v[154:157], v[2:3], off offset:768
	global_load_dwordx4 v[158:161], v[4:5], off offset:768
	global_load_dwordx4 v[162:165], v[2:3], off offset:832
	global_load_dwordx4 v[166:169], v[4:5], off offset:832
	s_waitcnt vmcnt(28)
	v_mfma_f32_16x16x32_bf16 v[8:11], v[170:173], v[174:177], v[8:11]
	v_mfma_f32_16x16x32_bf16 v[8:11], v[178:181], v[182:185], v[8:11]
	global_load_dwordx4 v[170:173], v[2:3], off offset:896
	global_load_dwordx4 v[174:177], v[4:5], off offset:896
	global_load_dwordx4 v[178:181], v[2:3], off offset:960
	global_load_dwordx4 v[182:185], v[4:5], off offset:960
	s_sub_i32 s8, s8, 1
	s_cmp_lg_u32 s8, 0
	s_cbranch_scc1 .Lctxo_loop
	s_waitcnt vmcnt(28)
	v_mfma_f32_16x16x32_bf16 v[8:11], v[58:61], v[62:65], v[8:11]
	v_mfma_f32_16x16x32_bf16 v[8:11], v[66:69], v[70:73], v[8:11]
	s_waitcnt vmcnt(24)
	v_mfma_f32_16x16x32_bf16 v[8:11], v[74:77], v[78:81], v[8:11]
	v_mfma_f32_16x16x32_bf16 v[8:11], v[82:85], v[86:89], v[8:11]
	s_waitcnt vmcnt(20)
	v_mfma_f32_16x16x32_bf16 v[8:11], v[90:93], v[94:97], v[8:11]
	v_mfma_f32_16x16x32_bf16 v[8:11], v[98:101], v[102:105], v[8:11]
	s_waitcnt vmcnt(16)
	v_mfma_f32_16x16x32_bf16 v[8:11], v[106:109], v[110:113], v[8:11]
	v_mfma_f32_16x16x32_bf16 v[8:11], v[114:117], v[118:121], v[8:11]
	s_waitcnt vmcnt(12)
	v_mfma_f32_16x16x32_bf16 v[8:11], v[122:125], v[126:129], v[8:11]
	v_mfma_f32_16x16x32_bf16 v[8:11], v[130:133], v[134:137], v[8:11]
	s_waitcnt vmcnt(8)
	v_mfma_f32_16x16x32_bf16 v[8:11], v[138:141], v[142:145], v[8:11]
	v_mfma_f32_16x16x32_bf16 v[8:11], v[146:149], v[150:153], v[8:11]
	s_waitcnt vmcnt(4)
	v_mfma_f32_16x16x32_bf16 v[8:11], v[154:157], v[158:161], v[8:11]
	v_mfma_f32_16x16x32_bf16 v[8:11], v[162:165], v[166:169], v[8:11]
	s_waitcnt vmcnt(0)
	v_mfma_f32_16x16x32_bf16 v[8:11], v[170:173], v[174:177], v[8:11]
	v_mfma_f32_16x16x32_bf16 v[8:11], v[178:181], v[182:185], v[8:11]
	s_nop 9
	v_cvt_pk_bf16_f32 v12, v8, v9
	v_cvt_pk_bf16_f32 v13, v10, v11
	global_store_dwordx2 v[6:7], v[12:13], off
	s_branch .LBB0_93
